# hyena_filters first MLP layer: weight column loaded once with batched loads, batched LDS row reads (was 66 serialized global round trips per item)
# speedup vs baseline: 1.0241x; 1.0046x over previous
.LBB0_947:
	s_or_b64 exec, exec, s[16:17]
	s_waitcnt lgkmcnt(0)
	s_barrier
	s_and_saveexec_b64 s[16:17], s[8:9]
	s_cbranch_execz .LBB0_952
	global_load_dword v0, v[144:145], off
	global_load_dword v1, v[142:143], off
	s_mov_b64 s[20:21], 0x1000
	v_lshl_add_u64 v[8:9], v[170:171], 0, s[20:21]
	v_lshl_add_u64 v[10:11], v[8:9], 0, s[20:21]
	global_load_dword v40, v[170:171], off
	global_load_dword v41, v[170:171], off offset:256
	global_load_dword v42, v[170:171], off offset:512
	global_load_dword v43, v[170:171], off offset:768
	global_load_dword v44, v[170:171], off offset:1024
	global_load_dword v45, v[170:171], off offset:1280
	global_load_dword v46, v[170:171], off offset:1536
	global_load_dword v47, v[170:171], off offset:1792
	global_load_dword v48, v[170:171], off offset:2048
	global_load_dword v49, v[170:171], off offset:2304
	global_load_dword v50, v[170:171], off offset:2560
	global_load_dword v51, v[170:171], off offset:2816
	global_load_dword v52, v[170:171], off offset:3072
	global_load_dword v53, v[170:171], off offset:3328
	global_load_dword v54, v[170:171], off offset:3584
	global_load_dword v55, v[170:171], off offset:3840
	global_load_dword v56, v[8:9], off
	global_load_dword v57, v[8:9], off offset:256
	global_load_dword v58, v[8:9], off offset:512
	global_load_dword v59, v[8:9], off offset:768
	global_load_dword v60, v[8:9], off offset:1024
	global_load_dword v61, v[8:9], off offset:1280
	global_load_dword v62, v[8:9], off offset:1536
	global_load_dword v63, v[8:9], off offset:1792
	global_load_dword v64, v[8:9], off offset:2048
	global_load_dword v65, v[8:9], off offset:2304
	global_load_dword v66, v[8:9], off offset:2560
	global_load_dword v67, v[8:9], off offset:2816
	global_load_dword v68, v[8:9], off offset:3072
	global_load_dword v69, v[8:9], off offset:3328
	global_load_dword v70, v[8:9], off offset:3584
	global_load_dword v71, v[8:9], off offset:3840
	global_load_dword v72, v[10:11], off
	v_mov_b32_e32 v2, v113
	s_movk_i32 s0, 0x84
	v_ashrrev_i32_e32 v3, 6, v2
	v_mul_lo_u32 v3, v3, s0
	v_add_u32_e32 v3, 0, v3
	ds_read2_b32 v[74:75], v3 offset1:1
	ds_read2_b32 v[76:77], v3 offset0:2 offset1:3
	ds_read2_b32 v[78:79], v3 offset0:4 offset1:5
	ds_read2_b32 v[80:81], v3 offset0:6 offset1:7
	ds_read2_b32 v[82:83], v3 offset0:8 offset1:9
	ds_read2_b32 v[84:85], v3 offset0:10 offset1:11
	ds_read2_b32 v[86:87], v3 offset0:12 offset1:13
	ds_read2_b32 v[88:89], v3 offset0:14 offset1:15
	ds_read2_b32 v[90:91], v3 offset0:16 offset1:17
	ds_read2_b32 v[92:93], v3 offset0:18 offset1:19
	ds_read2_b32 v[94:95], v3 offset0:20 offset1:21
	ds_read2_b32 v[96:97], v3 offset0:22 offset1:23
	ds_read2_b32 v[98:99], v3 offset0:24 offset1:25
	ds_read2_b32 v[100:101], v3 offset0:26 offset1:27
	ds_read2_b32 v[102:103], v3 offset0:28 offset1:29
	ds_read2_b32 v[104:105], v3 offset0:30 offset1:31
	ds_read_b32 v106, v3 offset:128
	s_waitcnt vmcnt(0) lgkmcnt(0)
	v_mov_b32_e32 v4, v0
	v_fmac_f32_e32 v4, v74, v40
	v_fmac_f32_e32 v4, v75, v41
	v_fmac_f32_e32 v4, v76, v42
	v_fmac_f32_e32 v4, v77, v43
	v_fmac_f32_e32 v4, v78, v44
	v_fmac_f32_e32 v4, v79, v45
	v_fmac_f32_e32 v4, v80, v46
	v_fmac_f32_e32 v4, v81, v47
	v_fmac_f32_e32 v4, v82, v48
	v_fmac_f32_e32 v4, v83, v49
	v_fmac_f32_e32 v4, v84, v50
	v_fmac_f32_e32 v4, v85, v51
	v_fmac_f32_e32 v4, v86, v52
	v_fmac_f32_e32 v4, v87, v53
	v_fmac_f32_e32 v4, v88, v54
	v_fmac_f32_e32 v4, v89, v55
	v_fmac_f32_e32 v4, v90, v56
	v_fmac_f32_e32 v4, v91, v57
	v_fmac_f32_e32 v4, v92, v58
	v_fmac_f32_e32 v4, v93, v59
	v_fmac_f32_e32 v4, v94, v60
	v_fmac_f32_e32 v4, v95, v61
	v_fmac_f32_e32 v4, v96, v62
	v_fmac_f32_e32 v4, v97, v63
	v_fmac_f32_e32 v4, v98, v64
	v_fmac_f32_e32 v4, v99, v65
	v_fmac_f32_e32 v4, v100, v66
	v_fmac_f32_e32 v4, v101, v67
	v_fmac_f32_e32 v4, v102, v68
	v_fmac_f32_e32 v4, v103, v69
	v_fmac_f32_e32 v4, v104, v70
	v_fmac_f32_e32 v4, v105, v71
	v_fmac_f32_e32 v4, v106, v72
	v_mul_f32_e32 v3, v1, v4
	v_mul_f32_e32 v4, 0.15915494, v3
	v_rndne_f32_e32 v4, v4
	v_fma_f32 v3, v3, 0.15915494, -v4
	v_sin_f32_e32 v3, v3
	v_lshl_add_u32 v4, v2, 2, 0
	v_add_u32_e32 v2, 0x200, v2
	s_nop 0
	ds_write_b32 v4, v3 offset:2112
	v_ashrrev_i32_e32 v3, 6, v2
	v_mul_lo_u32 v3, v3, s0
	v_add_u32_e32 v3, 0, v3
	ds_read2_b32 v[74:75], v3 offset1:1
	ds_read2_b32 v[76:77], v3 offset0:2 offset1:3
	ds_read2_b32 v[78:79], v3 offset0:4 offset1:5
	ds_read2_b32 v[80:81], v3 offset0:6 offset1:7
	ds_read2_b32 v[82:83], v3 offset0:8 offset1:9
	ds_read2_b32 v[84:85], v3 offset0:10 offset1:11
	ds_read2_b32 v[86:87], v3 offset0:12 offset1:13
	ds_read2_b32 v[88:89], v3 offset0:14 offset1:15
	ds_read2_b32 v[90:91], v3 offset0:16 offset1:17
	ds_read2_b32 v[92:93], v3 offset0:18 offset1:19
	ds_read2_b32 v[94:95], v3 offset0:20 offset1:21
	ds_read2_b32 v[96:97], v3 offset0:22 offset1:23
	ds_read2_b32 v[98:99], v3 offset0:24 offset1:25
	ds_read2_b32 v[100:101], v3 offset0:26 offset1:27
	ds_read2_b32 v[102:103], v3 offset0:28 offset1:29
	ds_read2_b32 v[104:105], v3 offset0:30 offset1:31
	ds_read_b32 v106, v3 offset:128
	s_waitcnt vmcnt(0) lgkmcnt(0)
	v_mov_b32_e32 v4, v0
	v_fmac_f32_e32 v4, v74, v40
	v_fmac_f32_e32 v4, v75, v41
	v_fmac_f32_e32 v4, v76, v42
	v_fmac_f32_e32 v4, v77, v43
	v_fmac_f32_e32 v4, v78, v44
	v_fmac_f32_e32 v4, v79, v45
	v_fmac_f32_e32 v4, v80, v46
	v_fmac_f32_e32 v4, v81, v47
	v_fmac_f32_e32 v4, v82, v48
	v_fmac_f32_e32 v4, v83, v49
	v_fmac_f32_e32 v4, v84, v50
	v_fmac_f32_e32 v4, v85, v51
	v_fmac_f32_e32 v4, v86, v52
	v_fmac_f32_e32 v4, v87, v53
	v_fmac_f32_e32 v4, v88, v54
	v_fmac_f32_e32 v4, v89, v55
	v_fmac_f32_e32 v4, v90, v56
	v_fmac_f32_e32 v4, v91, v57
	v_fmac_f32_e32 v4, v92, v58
	v_fmac_f32_e32 v4, v93, v59
	v_fmac_f32_e32 v4, v94, v60
	v_fmac_f32_e32 v4, v95, v61
	v_fmac_f32_e32 v4, v96, v62
	v_fmac_f32_e32 v4, v97, v63
	v_fmac_f32_e32 v4, v98, v64
	v_fmac_f32_e32 v4, v99, v65
	v_fmac_f32_e32 v4, v100, v66
	v_fmac_f32_e32 v4, v101, v67
	v_fmac_f32_e32 v4, v102, v68
	v_fmac_f32_e32 v4, v103, v69
	v_fmac_f32_e32 v4, v104, v70
	v_fmac_f32_e32 v4, v105, v71
	v_fmac_f32_e32 v4, v106, v72
	v_mul_f32_e32 v3, v1, v4
	v_mul_f32_e32 v4, 0.15915494, v3
	v_rndne_f32_e32 v4, v4
	v_fma_f32 v3, v3, 0.15915494, -v4
	v_sin_f32_e32 v3, v3
	v_lshl_add_u32 v4, v2, 2, 0
	v_add_u32_e32 v2, 0x200, v2
	s_nop 0
	ds_write_b32 v4, v3 offset:2112
